# grid barrier: non-leader workgroups poll the cross-XCD release word directly, leader's per-XCD forward dropped
# speedup vs baseline: 1.0030x; 1.0030x over previous
; __device__ __forceinline__ unsigned xb_ld(unsigned* p)              { return __hip_atomic_load(p, __ATOMIC_RELAXED, __HIP_MEMORY_SCOPE_AGENT); }
; __device__ __forceinline__ unsigned xb_add(unsigned* p, unsigned v) { return __hip_atomic_fetch_add(p, v, __ATOMIC_RELAXED, __HIP_MEMORY_SCOPE_AGENT); }
; #define XB_SPIN(cond, bar) do { unsigned _sp = 0; while (cond) { __builtin_amdgcn_s_sleep(1); \
;     if ((++_sp & 255u) == 0u) { if (xb_ld(&(bar)[XB_TMO])) break; if (_sp > XB_SPIN_CAP) { atomicAdd(&(bar)[XB_TMO], 1u); break; } } } } while (0)
; __device__ __forceinline__ void xcd_barrier(const XcdBarrier& b) {
;     ...
;         unsigned nloc = b.st[0], nx = b.st[1];
;         if (nloc == 0u) { xcd_barrier_complete(bar, b.x, nloc, nx); b.st[0] = nloc; b.st[1] = nx; }
;         const unsigned old = xb_add(&bar[XB_XSUB(b.x)], 1u);
;         const unsigned gen = old / nloc;
;         if (old + 1u == (gen + 1u) * nloc) {
;     ...
;             XB_SPIN(xb_ld(&bar[XB_XGEN(b.x)]) == gen, bar);
.LBB0_236:
	s_or_b64 exec, exec, s[8:9]
	v_cvt_f32_u32_e32 v4, v2
	s_waitcnt vmcnt(0)
	v_readfirstlane_b32 s6, v3
	v_sub_u32_e32 v3, 0, v2
	v_rcp_iflag_f32_e32 v4, v4
	v_add_u32_e32 v5, s6, v1
	v_mul_f32_e32 v4, 0x4f7ffffe, v4
	v_cvt_u32_f32_e32 v4, v4
	v_mul_lo_u32 v1, v3, v4
	v_mul_hi_u32 v1, v4, v1
	v_add_u32_e32 v1, v4, v1
	v_mul_hi_u32 v1, v5, v1
	v_mul_lo_u32 v3, v1, v2
	v_sub_u32_e32 v3, v5, v3
	v_add_u32_e32 v4, 1, v1
	v_cmp_ge_u32_e32 vcc, v3, v2
	s_nop 1
	v_cndmask_b32_e32 v1, v1, v4, vcc
	v_sub_u32_e32 v4, v3, v2
	v_cndmask_b32_e32 v3, v3, v4, vcc
	v_add_u32_e32 v4, 1, v1
	v_cmp_ge_u32_e32 vcc, v3, v2
	v_add_u32_e32 v3, 1, v5
	s_nop 0
	v_cndmask_b32_e32 v1, v1, v4, vcc
	v_mul_lo_u32 v4, v2, v1
	v_add_u32_e32 v2, v4, v2
	v_cmp_ne_u32_e32 vcc, v3, v2
	s_and_saveexec_b64 s[6:7], vcc
	s_xor_b64 s[6:7], exec, s[6:7]
	s_cbranch_execz .LBB0_250
	s_waitcnt lgkmcnt(0)
	v_mov_b32_e32 v0, 0
	s_add_u32 s12, s88, 0x803500
	s_addc_u32 s13, s89, 0
	global_load_dword v0, v0, s[12:13] sc1
	s_waitcnt vmcnt(0)
	v_cmp_eq_u32_e32 vcc, v0, v1
	s_and_saveexec_b64 s[8:9], vcc
	s_cbranch_execz .LBB0_249
	s_add_u32 s10, s88, 0x800200
	s_addc_u32 s11, s89, 0
	s_mov_b32 s33, 1
	s_mov_b64 s[14:15], 0
	v_mov_b32_e32 v0, 0
	s_branch .LBB0_240

; __device__ __forceinline__ unsigned xb_add(unsigned* p, unsigned v) { return __hip_atomic_fetch_add(p, v, __ATOMIC_RELAXED, __HIP_MEMORY_SCOPE_AGENT); }
; __device__ __forceinline__ void xcd_barrier(const XcdBarrier& b) {
;     ...
;             __builtin_amdgcn_fence(__ATOMIC_ACQUIRE, "agent");
;             xb_add(&bar[XB_XGEN(b.x)], 1u);
;             asm volatile("s_waitcnt vmcnt(0)" ::: "memory");
.LBB0_267:
	s_or_b64 exec, exec, s[6:7]
	s_mov_b64 s[6:7], exec
	v_mbcnt_lo_u32_b32 v0, s6, 0
	v_mbcnt_hi_u32_b32 v0, s7, v0
	v_cmp_eq_u32_e32 vcc, 0, v0
	s_waitcnt vmcnt(0)
	buffer_inv sc1
	s_and_saveexec_b64 s[8:9], vcc
	s_cbranch_execz .LBB0_269
	s_bcnt1_i32_b64 s6, s[6:7]
	v_mov_b32_e32 v0, 0x2000
	v_mov_b32_e32 v1, s6
.LBB0_269:
	s_or_b64 exec, exec, s[8:9]
	s_waitcnt vmcnt(0)

; __device__ __forceinline__ unsigned xb_ld(unsigned* p)              { return __hip_atomic_load(p, __ATOMIC_RELAXED, __HIP_MEMORY_SCOPE_AGENT); }
; __device__ __forceinline__ unsigned xb_add(unsigned* p, unsigned v) { return __hip_atomic_fetch_add(p, v, __ATOMIC_RELAXED, __HIP_MEMORY_SCOPE_AGENT); }
; #define XB_SPIN(cond, bar) do { unsigned _sp = 0; while (cond) { __builtin_amdgcn_s_sleep(1); \
;     if ((++_sp & 255u) == 0u) { if (xb_ld(&(bar)[XB_TMO])) break; if (_sp > XB_SPIN_CAP) { atomicAdd(&(bar)[XB_TMO], 1u); break; } } } } while (0)
; __device__ __forceinline__ void xcd_barrier(const XcdBarrier& b) {
;     ...
;         unsigned nloc = b.st[0], nx = b.st[1];
;         if (nloc == 0u) { xcd_barrier_complete(bar, b.x, nloc, nx); b.st[0] = nloc; b.st[1] = nx; }
;         const unsigned old = xb_add(&bar[XB_XSUB(b.x)], 1u);
;         const unsigned gen = old / nloc;
;         if (old + 1u == (gen + 1u) * nloc) {
;     ...
;             XB_SPIN(xb_ld(&bar[XB_XGEN(b.x)]) == gen, bar);
.LBB0_525:
	s_or_b64 exec, exec, s[8:9]
	v_cvt_f32_u32_e32 v4, v2
	s_waitcnt vmcnt(0)
	v_readfirstlane_b32 s6, v3
	v_sub_u32_e32 v3, 0, v2
	v_rcp_iflag_f32_e32 v4, v4
	v_add_u32_e32 v5, s6, v1
	v_mul_f32_e32 v4, 0x4f7ffffe, v4
	v_cvt_u32_f32_e32 v4, v4
	v_mul_lo_u32 v1, v3, v4
	v_mul_hi_u32 v1, v4, v1
	v_add_u32_e32 v1, v4, v1
	v_mul_hi_u32 v1, v5, v1
	v_mul_lo_u32 v3, v1, v2
	v_sub_u32_e32 v3, v5, v3
	v_add_u32_e32 v4, 1, v1
	v_cmp_ge_u32_e32 vcc, v3, v2
	s_nop 1
	v_cndmask_b32_e32 v1, v1, v4, vcc
	v_sub_u32_e32 v4, v3, v2
	v_cndmask_b32_e32 v3, v3, v4, vcc
	v_add_u32_e32 v4, 1, v1
	v_cmp_ge_u32_e32 vcc, v3, v2
	v_add_u32_e32 v3, 1, v5
	s_nop 0
	v_cndmask_b32_e32 v1, v1, v4, vcc
	v_mul_lo_u32 v4, v2, v1
	v_add_u32_e32 v2, v4, v2
	v_cmp_ne_u32_e32 vcc, v3, v2
	s_and_saveexec_b64 s[6:7], vcc
	s_xor_b64 s[6:7], exec, s[6:7]
	s_cbranch_execz .LBB0_539
	s_waitcnt lgkmcnt(0)
	v_mov_b32_e32 v0, 0
	s_add_u32 s14, s88, 0x803500
	s_addc_u32 s15, s89, 0
	global_load_dword v0, v0, s[14:15] sc1
	s_waitcnt vmcnt(0)
	v_cmp_eq_u32_e32 vcc, v0, v1
	s_and_saveexec_b64 s[8:9], vcc
	s_cbranch_execz .LBB0_538
	s_add_u32 s10, s88, 0x800200
	s_addc_u32 s11, s89, 0
	s_mov_b32 s33, 1
	s_mov_b64 s[16:17], 0
	v_mov_b32_e32 v0, 0
	s_branch .LBB0_529

; __device__ __forceinline__ unsigned xb_add(unsigned* p, unsigned v) { return __hip_atomic_fetch_add(p, v, __ATOMIC_RELAXED, __HIP_MEMORY_SCOPE_AGENT); }
; __device__ __forceinline__ void xcd_barrier(const XcdBarrier& b) {
;     ...
;             __builtin_amdgcn_fence(__ATOMIC_ACQUIRE, "agent");
;             xb_add(&bar[XB_XGEN(b.x)], 1u);
;             asm volatile("s_waitcnt vmcnt(0)" ::: "memory");
.LBB0_556:
	s_or_b64 exec, exec, s[6:7]
	s_mov_b64 s[6:7], exec
	v_mbcnt_lo_u32_b32 v0, s6, 0
	v_mbcnt_hi_u32_b32 v0, s7, v0
	v_cmp_eq_u32_e32 vcc, 0, v0
	s_waitcnt vmcnt(0)
	buffer_inv sc1
	s_and_saveexec_b64 s[8:9], vcc
	s_cbranch_execz .LBB0_558
	s_bcnt1_i32_b64 s6, s[6:7]
	v_mov_b32_e32 v0, 0x2000
	v_mov_b32_e32 v1, s6
.LBB0_558:
	s_or_b64 exec, exec, s[8:9]
	s_waitcnt vmcnt(0)

; __device__ __forceinline__ unsigned xb_ld(unsigned* p)              { return __hip_atomic_load(p, __ATOMIC_RELAXED, __HIP_MEMORY_SCOPE_AGENT); }
; __device__ __forceinline__ unsigned xb_add(unsigned* p, unsigned v) { return __hip_atomic_fetch_add(p, v, __ATOMIC_RELAXED, __HIP_MEMORY_SCOPE_AGENT); }
; #define XB_SPIN(cond, bar) do { unsigned _sp = 0; while (cond) { __builtin_amdgcn_s_sleep(1); \
;     if ((++_sp & 255u) == 0u) { if (xb_ld(&(bar)[XB_TMO])) break; if (_sp > XB_SPIN_CAP) { atomicAdd(&(bar)[XB_TMO], 1u); break; } } } } while (0)
; __device__ __forceinline__ void xcd_barrier(const XcdBarrier& b) {
;     ...
;         unsigned nloc = b.st[0], nx = b.st[1];
;         if (nloc == 0u) { xcd_barrier_complete(bar, b.x, nloc, nx); b.st[0] = nloc; b.st[1] = nx; }
;         const unsigned old = xb_add(&bar[XB_XSUB(b.x)], 1u);
;         const unsigned gen = old / nloc;
;         if (old + 1u == (gen + 1u) * nloc) {
;     ...
;             XB_SPIN(xb_ld(&bar[XB_XGEN(b.x)]) == gen, bar);
.LBB0_618:
	s_or_b64 exec, exec, s[10:11]
	v_cvt_f32_u32_e32 v4, v2
	s_waitcnt vmcnt(0)
	v_readfirstlane_b32 s2, v3
	v_sub_u32_e32 v3, 0, v2
	v_rcp_iflag_f32_e32 v4, v4
	v_add_u32_e32 v5, s2, v1
	v_mul_f32_e32 v4, 0x4f7ffffe, v4
	v_cvt_u32_f32_e32 v4, v4
	v_mul_lo_u32 v1, v3, v4
	v_mul_hi_u32 v1, v4, v1
	v_add_u32_e32 v1, v4, v1
	v_mul_hi_u32 v1, v5, v1
	v_mul_lo_u32 v3, v1, v2
	v_sub_u32_e32 v3, v5, v3
	v_add_u32_e32 v4, 1, v1
	v_cmp_ge_u32_e32 vcc, v3, v2
	s_nop 1
	v_cndmask_b32_e32 v1, v1, v4, vcc
	v_sub_u32_e32 v4, v3, v2
	v_cndmask_b32_e32 v3, v3, v4, vcc
	v_add_u32_e32 v4, 1, v1
	v_cmp_ge_u32_e32 vcc, v3, v2
	v_add_u32_e32 v3, 1, v5
	s_nop 0
	v_cndmask_b32_e32 v1, v1, v4, vcc
	v_mul_lo_u32 v4, v2, v1
	v_add_u32_e32 v2, v4, v2
	v_cmp_ne_u32_e32 vcc, v3, v2
	s_and_saveexec_b64 s[2:3], vcc
	s_xor_b64 s[8:9], exec, s[2:3]
	s_cbranch_execz .LBB0_632
	s_waitcnt lgkmcnt(0)
	v_mov_b32_e32 v0, 0
	s_add_u32 s14, s88, 0x803500
	s_addc_u32 s15, s89, 0
	global_load_dword v0, v0, s[14:15] sc1
	s_waitcnt vmcnt(0)
	v_cmp_eq_u32_e32 vcc, v0, v1
	s_and_saveexec_b64 s[10:11], vcc
	s_cbranch_execz .LBB0_631
	s_add_u32 s12, s88, 0x800200
	s_addc_u32 s13, s89, 0
	s_mov_b32 s2, 1
	s_mov_b64 s[16:17], 0
	v_mov_b32_e32 v0, 0
	s_branch .LBB0_622

; __device__ __forceinline__ unsigned xb_add(unsigned* p, unsigned v) { return __hip_atomic_fetch_add(p, v, __ATOMIC_RELAXED, __HIP_MEMORY_SCOPE_AGENT); }
; __device__ __forceinline__ void xcd_barrier(const XcdBarrier& b) {
;     ...
;             __builtin_amdgcn_fence(__ATOMIC_ACQUIRE, "agent");
;             xb_add(&bar[XB_XGEN(b.x)], 1u);
;             asm volatile("s_waitcnt vmcnt(0)" ::: "memory");
.LBB0_649:
	s_or_b64 exec, exec, s[8:9]
	s_mov_b64 s[8:9], exec
	v_mbcnt_lo_u32_b32 v0, s8, 0
	v_mbcnt_hi_u32_b32 v0, s9, v0
	v_cmp_eq_u32_e32 vcc, 0, v0
	s_waitcnt vmcnt(0)
	buffer_inv sc1
	s_and_saveexec_b64 s[10:11], vcc
	s_cbranch_execz .LBB0_651
	s_bcnt1_i32_b64 s2, s[8:9]
	v_mov_b32_e32 v0, 0x2000
	v_mov_b32_e32 v1, s2
.LBB0_651:
	s_or_b64 exec, exec, s[10:11]
	s_waitcnt vmcnt(0)

; __device__ __forceinline__ unsigned xb_ld(unsigned* p)              { return __hip_atomic_load(p, __ATOMIC_RELAXED, __HIP_MEMORY_SCOPE_AGENT); }
; __device__ __forceinline__ unsigned xb_add(unsigned* p, unsigned v) { return __hip_atomic_fetch_add(p, v, __ATOMIC_RELAXED, __HIP_MEMORY_SCOPE_AGENT); }
; #define XB_SPIN(cond, bar) do { unsigned _sp = 0; while (cond) { __builtin_amdgcn_s_sleep(1); \
;     if ((++_sp & 255u) == 0u) { if (xb_ld(&(bar)[XB_TMO])) break; if (_sp > XB_SPIN_CAP) { atomicAdd(&(bar)[XB_TMO], 1u); break; } } } } while (0)
; __device__ __forceinline__ void xcd_barrier(const XcdBarrier& b) {
;     ...
;         unsigned nloc = b.st[0], nx = b.st[1];
;         if (nloc == 0u) { xcd_barrier_complete(bar, b.x, nloc, nx); b.st[0] = nloc; b.st[1] = nx; }
;         const unsigned old = xb_add(&bar[XB_XSUB(b.x)], 1u);
;         const unsigned gen = old / nloc;
;         if (old + 1u == (gen + 1u) * nloc) {
;     ...
;             XB_SPIN(xb_ld(&bar[XB_XGEN(b.x)]) == gen, bar);
.LBB0_705:
	s_or_b64 exec, exec, s[24:25]
	v_cvt_f32_u32_e32 v4, v2
	s_waitcnt vmcnt(0)
	v_readfirstlane_b32 s2, v3
	v_sub_u32_e32 v3, 0, v2
	v_rcp_iflag_f32_e32 v4, v4
	v_add_u32_e32 v5, s2, v1
	v_mul_f32_e32 v4, 0x4f7ffffe, v4
	v_cvt_u32_f32_e32 v4, v4
	v_mul_lo_u32 v1, v3, v4
	v_mul_hi_u32 v1, v4, v1
	v_add_u32_e32 v1, v4, v1
	v_mul_hi_u32 v1, v5, v1
	v_mul_lo_u32 v3, v1, v2
	v_sub_u32_e32 v3, v5, v3
	v_add_u32_e32 v4, 1, v1
	v_cmp_ge_u32_e32 vcc, v3, v2
	s_nop 1
	v_cndmask_b32_e32 v1, v1, v4, vcc
	v_sub_u32_e32 v4, v3, v2
	v_cndmask_b32_e32 v3, v3, v4, vcc
	v_add_u32_e32 v4, 1, v1
	v_cmp_ge_u32_e32 vcc, v3, v2
	v_add_u32_e32 v3, 1, v5
	s_nop 0
	v_cndmask_b32_e32 v1, v1, v4, vcc
	v_mul_lo_u32 v4, v2, v1
	v_add_u32_e32 v2, v4, v2
	v_cmp_ne_u32_e32 vcc, v3, v2
	s_and_saveexec_b64 s[2:3], vcc
	s_xor_b64 s[8:9], exec, s[2:3]
	s_cbranch_execz .LBB0_719
	s_waitcnt lgkmcnt(0)
	v_mov_b32_e32 v0, 0
	s_add_u32 s28, s88, 0x803500
	s_addc_u32 s29, s89, 0
	global_load_dword v0, v0, s[28:29] sc1
	s_waitcnt vmcnt(0)
	v_cmp_eq_u32_e32 vcc, v0, v1
	s_and_saveexec_b64 s[24:25], vcc
	s_cbranch_execz .LBB0_718
	s_add_u32 s26, s88, 0x800200
	s_addc_u32 s27, s89, 0
	s_mov_b32 s2, 1
	s_mov_b64 s[30:31], 0
	v_mov_b32_e32 v0, 0
	s_branch .LBB0_709

; __device__ __forceinline__ unsigned xb_add(unsigned* p, unsigned v) { return __hip_atomic_fetch_add(p, v, __ATOMIC_RELAXED, __HIP_MEMORY_SCOPE_AGENT); }
; __device__ __forceinline__ void xcd_barrier(const XcdBarrier& b) {
;     ...
;             __builtin_amdgcn_fence(__ATOMIC_ACQUIRE, "agent");
;             xb_add(&bar[XB_XGEN(b.x)], 1u);
;             asm volatile("s_waitcnt vmcnt(0)" ::: "memory");
.LBB0_736:
	s_or_b64 exec, exec, s[8:9]
	s_mov_b64 s[8:9], exec
	v_mbcnt_lo_u32_b32 v0, s8, 0
	v_mbcnt_hi_u32_b32 v0, s9, v0
	v_cmp_eq_u32_e32 vcc, 0, v0
	s_waitcnt vmcnt(0)
	buffer_inv sc1
	s_and_saveexec_b64 s[24:25], vcc
	s_cbranch_execz .LBB0_738
	s_bcnt1_i32_b64 s2, s[8:9]
	v_mov_b32_e32 v0, 0x2000
	v_mov_b32_e32 v1, s2
.LBB0_738:
	s_or_b64 exec, exec, s[24:25]
	s_waitcnt vmcnt(0)

; __device__ __forceinline__ unsigned xb_ld(unsigned* p)              { return __hip_atomic_load(p, __ATOMIC_RELAXED, __HIP_MEMORY_SCOPE_AGENT); }
; __device__ __forceinline__ unsigned xb_add(unsigned* p, unsigned v) { return __hip_atomic_fetch_add(p, v, __ATOMIC_RELAXED, __HIP_MEMORY_SCOPE_AGENT); }
; #define XB_SPIN(cond, bar) do { unsigned _sp = 0; while (cond) { __builtin_amdgcn_s_sleep(1); \
;     if ((++_sp & 255u) == 0u) { if (xb_ld(&(bar)[XB_TMO])) break; if (_sp > XB_SPIN_CAP) { atomicAdd(&(bar)[XB_TMO], 1u); break; } } } } while (0)
; __device__ __forceinline__ void xcd_barrier(const XcdBarrier& b) {
;     ...
;         unsigned nloc = b.st[0], nx = b.st[1];
;         if (nloc == 0u) { xcd_barrier_complete(bar, b.x, nloc, nx); b.st[0] = nloc; b.st[1] = nx; }
;         const unsigned old = xb_add(&bar[XB_XSUB(b.x)], 1u);
;         const unsigned gen = old / nloc;
;         if (old + 1u == (gen + 1u) * nloc) {
;     ...
;             XB_SPIN(xb_ld(&bar[XB_XGEN(b.x)]) == gen, bar);
.LBB0_830:
	s_or_b64 exec, exec, s[8:9]
	v_cvt_f32_u32_e32 v4, v2
	s_waitcnt vmcnt(0)
	v_readfirstlane_b32 s6, v3
	v_sub_u32_e32 v3, 0, v2
	v_rcp_iflag_f32_e32 v4, v4
	v_add_u32_e32 v5, s6, v1
	v_mul_f32_e32 v4, 0x4f7ffffe, v4
	v_cvt_u32_f32_e32 v4, v4
	v_mul_lo_u32 v1, v3, v4
	v_mul_hi_u32 v1, v4, v1
	v_add_u32_e32 v1, v4, v1
	v_mul_hi_u32 v1, v5, v1
	v_mul_lo_u32 v3, v1, v2
	v_sub_u32_e32 v3, v5, v3
	v_add_u32_e32 v4, 1, v1
	v_cmp_ge_u32_e32 vcc, v3, v2
	s_nop 1
	v_cndmask_b32_e32 v1, v1, v4, vcc
	v_sub_u32_e32 v4, v3, v2
	v_cndmask_b32_e32 v3, v3, v4, vcc
	v_add_u32_e32 v4, 1, v1
	v_cmp_ge_u32_e32 vcc, v3, v2
	v_add_u32_e32 v3, 1, v5
	s_nop 0
	v_cndmask_b32_e32 v1, v1, v4, vcc
	v_mul_lo_u32 v4, v2, v1
	v_add_u32_e32 v2, v4, v2
	v_cmp_ne_u32_e32 vcc, v3, v2
	s_and_saveexec_b64 s[6:7], vcc
	s_xor_b64 s[6:7], exec, s[6:7]
	s_cbranch_execz .LBB0_844
	s_waitcnt lgkmcnt(0)
	v_mov_b32_e32 v0, 0
	s_add_u32 s16, s88, 0x803500
	s_addc_u32 s17, s89, 0
	global_load_dword v0, v0, s[16:17] sc1
	s_waitcnt vmcnt(0)
	v_cmp_eq_u32_e32 vcc, v0, v1
	s_and_saveexec_b64 s[8:9], vcc
	s_cbranch_execz .LBB0_843
	s_add_u32 s14, s88, 0x800200
	s_addc_u32 s15, s89, 0
	s_mov_b32 s28, 1
	s_mov_b64 s[18:19], 0
	v_mov_b32_e32 v0, 0
	s_branch .LBB0_834

; __device__ __forceinline__ unsigned xb_add(unsigned* p, unsigned v) { return __hip_atomic_fetch_add(p, v, __ATOMIC_RELAXED, __HIP_MEMORY_SCOPE_AGENT); }
; __device__ __forceinline__ void xcd_barrier(const XcdBarrier& b) {
;     ...
;             __builtin_amdgcn_fence(__ATOMIC_ACQUIRE, "agent");
;             xb_add(&bar[XB_XGEN(b.x)], 1u);
;             asm volatile("s_waitcnt vmcnt(0)" ::: "memory");
.LBB0_861:
	s_or_b64 exec, exec, s[6:7]
	s_mov_b64 s[6:7], exec
	v_mbcnt_lo_u32_b32 v0, s6, 0
	v_mbcnt_hi_u32_b32 v0, s7, v0
	v_cmp_eq_u32_e32 vcc, 0, v0
	s_waitcnt vmcnt(0)
	buffer_inv sc1
	s_and_saveexec_b64 s[8:9], vcc
	s_cbranch_execz .LBB0_863
	s_bcnt1_i32_b64 s6, s[6:7]
	v_mov_b32_e32 v0, 0x2000
	v_mov_b32_e32 v1, s6
.LBB0_863:
	s_or_b64 exec, exec, s[8:9]
	s_waitcnt vmcnt(0)

; __device__ __forceinline__ unsigned xb_ld(unsigned* p)              { return __hip_atomic_load(p, __ATOMIC_RELAXED, __HIP_MEMORY_SCOPE_AGENT); }
; __device__ __forceinline__ unsigned xb_add(unsigned* p, unsigned v) { return __hip_atomic_fetch_add(p, v, __ATOMIC_RELAXED, __HIP_MEMORY_SCOPE_AGENT); }
; #define XB_SPIN(cond, bar) do { unsigned _sp = 0; while (cond) { __builtin_amdgcn_s_sleep(1); \
;     if ((++_sp & 255u) == 0u) { if (xb_ld(&(bar)[XB_TMO])) break; if (_sp > XB_SPIN_CAP) { atomicAdd(&(bar)[XB_TMO], 1u); break; } } } } while (0)
; __device__ __forceinline__ void xcd_barrier(const XcdBarrier& b) {
;     ...
;         unsigned nloc = b.st[0], nx = b.st[1];
;         if (nloc == 0u) { xcd_barrier_complete(bar, b.x, nloc, nx); b.st[0] = nloc; b.st[1] = nx; }
;         const unsigned old = xb_add(&bar[XB_XSUB(b.x)], 1u);
;         const unsigned gen = old / nloc;
;         if (old + 1u == (gen + 1u) * nloc) {
;     ...
;             XB_SPIN(xb_ld(&bar[XB_XGEN(b.x)]) == gen, bar);
.LBB0_909:
	s_or_b64 exec, exec, s[8:9]
	v_cvt_f32_u32_e32 v4, v2
	s_waitcnt vmcnt(0)
	v_readfirstlane_b32 s6, v3
	v_sub_u32_e32 v3, 0, v2
	v_rcp_iflag_f32_e32 v4, v4
	v_add_u32_e32 v5, s6, v1
	v_mul_f32_e32 v4, 0x4f7ffffe, v4
	v_cvt_u32_f32_e32 v4, v4
	v_mul_lo_u32 v1, v3, v4
	v_mul_hi_u32 v1, v4, v1
	v_add_u32_e32 v1, v4, v1
	v_mul_hi_u32 v1, v5, v1
	v_mul_lo_u32 v3, v1, v2
	v_sub_u32_e32 v3, v5, v3
	v_add_u32_e32 v4, 1, v1
	v_cmp_ge_u32_e32 vcc, v3, v2
	s_nop 1
	v_cndmask_b32_e32 v1, v1, v4, vcc
	v_sub_u32_e32 v4, v3, v2
	v_cndmask_b32_e32 v3, v3, v4, vcc
	v_add_u32_e32 v4, 1, v1
	v_cmp_ge_u32_e32 vcc, v3, v2
	v_add_u32_e32 v3, 1, v5
	s_nop 0
	v_cndmask_b32_e32 v1, v1, v4, vcc
	v_mul_lo_u32 v4, v2, v1
	v_add_u32_e32 v2, v4, v2
	v_cmp_ne_u32_e32 vcc, v3, v2
	s_and_saveexec_b64 s[6:7], vcc
	s_xor_b64 s[6:7], exec, s[6:7]
	s_cbranch_execz .LBB0_923
	s_waitcnt lgkmcnt(0)
	v_mov_b32_e32 v0, 0
	s_add_u32 s14, s88, 0x803500
	s_addc_u32 s15, s89, 0
	global_load_dword v0, v0, s[14:15] sc1
	s_waitcnt vmcnt(0)
	v_cmp_eq_u32_e32 vcc, v0, v1
	s_and_saveexec_b64 s[8:9], vcc
	s_cbranch_execz .LBB0_922
	s_add_u32 s12, s88, 0x800200
	s_addc_u32 s13, s89, 0
	s_mov_b32 s26, 1
	s_mov_b64 s[16:17], 0
	v_mov_b32_e32 v0, 0
	s_branch .LBB0_913

; __device__ __forceinline__ unsigned xb_add(unsigned* p, unsigned v) { return __hip_atomic_fetch_add(p, v, __ATOMIC_RELAXED, __HIP_MEMORY_SCOPE_AGENT); }
; __device__ __forceinline__ void xcd_barrier(const XcdBarrier& b) {
;     ...
;             __builtin_amdgcn_fence(__ATOMIC_ACQUIRE, "agent");
;             xb_add(&bar[XB_XGEN(b.x)], 1u);
;             asm volatile("s_waitcnt vmcnt(0)" ::: "memory");
.LBB0_940:
	s_or_b64 exec, exec, s[6:7]
	s_mov_b64 s[6:7], exec
	v_mbcnt_lo_u32_b32 v0, s6, 0
	v_mbcnt_hi_u32_b32 v0, s7, v0
	v_cmp_eq_u32_e32 vcc, 0, v0
	s_waitcnt vmcnt(0)
	buffer_inv sc1
	s_and_saveexec_b64 s[8:9], vcc
	s_cbranch_execz .LBB0_942
	s_bcnt1_i32_b64 s6, s[6:7]
	v_mov_b32_e32 v0, 0x2000
	v_mov_b32_e32 v1, s6
.LBB0_942:
	s_or_b64 exec, exec, s[8:9]
	s_waitcnt vmcnt(0)

; __device__ __forceinline__ unsigned xb_ld(unsigned* p)              { return __hip_atomic_load(p, __ATOMIC_RELAXED, __HIP_MEMORY_SCOPE_AGENT); }
; __device__ __forceinline__ unsigned xb_add(unsigned* p, unsigned v) { return __hip_atomic_fetch_add(p, v, __ATOMIC_RELAXED, __HIP_MEMORY_SCOPE_AGENT); }
; #define XB_SPIN(cond, bar) do { unsigned _sp = 0; while (cond) { __builtin_amdgcn_s_sleep(1); \
;     if ((++_sp & 255u) == 0u) { if (xb_ld(&(bar)[XB_TMO])) break; if (_sp > XB_SPIN_CAP) { atomicAdd(&(bar)[XB_TMO], 1u); break; } } } } while (0)
; __device__ __forceinline__ void xcd_barrier(const XcdBarrier& b) {
;     ...
;         unsigned nloc = b.st[0], nx = b.st[1];
;         if (nloc == 0u) { xcd_barrier_complete(bar, b.x, nloc, nx); b.st[0] = nloc; b.st[1] = nx; }
;         const unsigned old = xb_add(&bar[XB_XSUB(b.x)], 1u);
;         const unsigned gen = old / nloc;
;         if (old + 1u == (gen + 1u) * nloc) {
;     ...
;             XB_SPIN(xb_ld(&bar[XB_XGEN(b.x)]) == gen, bar);
.LBB0_1006:
	s_or_b64 exec, exec, s[8:9]
	v_cvt_f32_u32_e32 v4, v2
	s_waitcnt vmcnt(0)
	v_readfirstlane_b32 s6, v3
	v_sub_u32_e32 v3, 0, v2
	v_rcp_iflag_f32_e32 v4, v4
	v_add_u32_e32 v5, s6, v1
	v_mul_f32_e32 v4, 0x4f7ffffe, v4
	v_cvt_u32_f32_e32 v4, v4
	v_mul_lo_u32 v1, v3, v4
	v_mul_hi_u32 v1, v4, v1
	v_add_u32_e32 v1, v4, v1
	v_mul_hi_u32 v1, v5, v1
	v_mul_lo_u32 v3, v1, v2
	v_sub_u32_e32 v3, v5, v3
	v_add_u32_e32 v4, 1, v1
	v_cmp_ge_u32_e32 vcc, v3, v2
	s_nop 1
	v_cndmask_b32_e32 v1, v1, v4, vcc
	v_sub_u32_e32 v4, v3, v2
	v_cndmask_b32_e32 v3, v3, v4, vcc
	v_add_u32_e32 v4, 1, v1
	v_cmp_ge_u32_e32 vcc, v3, v2
	v_add_u32_e32 v3, 1, v5
	s_nop 0
	v_cndmask_b32_e32 v1, v1, v4, vcc
	v_mul_lo_u32 v4, v2, v1
	v_add_u32_e32 v2, v4, v2
	v_cmp_ne_u32_e32 vcc, v3, v2
	s_and_saveexec_b64 s[6:7], vcc
	s_xor_b64 s[6:7], exec, s[6:7]
	s_cbranch_execz .LBB0_1020
	s_waitcnt lgkmcnt(0)
	v_mov_b32_e32 v0, 0
	s_add_u32 s12, s88, 0x803500
	s_addc_u32 s13, s89, 0
	global_load_dword v0, v0, s[12:13] sc1
	s_waitcnt vmcnt(0)
	v_cmp_eq_u32_e32 vcc, v0, v1
	s_and_saveexec_b64 s[8:9], vcc
	s_cbranch_execz .LBB0_1019
	s_add_u32 s10, s88, 0x800200
	s_addc_u32 s11, s89, 0
	s_mov_b32 s24, 1
	s_mov_b64 s[14:15], 0
	v_mov_b32_e32 v0, 0
	s_branch .LBB0_1010

; __device__ __forceinline__ unsigned xb_add(unsigned* p, unsigned v) { return __hip_atomic_fetch_add(p, v, __ATOMIC_RELAXED, __HIP_MEMORY_SCOPE_AGENT); }
; __device__ __forceinline__ void xcd_barrier(const XcdBarrier& b) {
;     ...
;             __builtin_amdgcn_fence(__ATOMIC_ACQUIRE, "agent");
;             xb_add(&bar[XB_XGEN(b.x)], 1u);
;             asm volatile("s_waitcnt vmcnt(0)" ::: "memory");
.LBB0_1037:
	s_or_b64 exec, exec, s[6:7]
	s_mov_b64 s[6:7], exec
	v_mbcnt_lo_u32_b32 v0, s6, 0
	v_mbcnt_hi_u32_b32 v0, s7, v0
	v_cmp_eq_u32_e32 vcc, 0, v0
	s_waitcnt vmcnt(0)
	buffer_inv sc1
	s_and_saveexec_b64 s[8:9], vcc
	s_cbranch_execz .LBB0_1039
	s_bcnt1_i32_b64 s6, s[6:7]
	v_mov_b32_e32 v0, 0x2000
	v_mov_b32_e32 v1, s6
.LBB0_1039:
	s_or_b64 exec, exec, s[8:9]
	s_waitcnt vmcnt(0)

; __device__ __forceinline__ unsigned xb_add(unsigned* p, unsigned v) { return __hip_atomic_fetch_add(p, v, __ATOMIC_RELAXED, __HIP_MEMORY_SCOPE_AGENT); }
; __device__ __forceinline__ void xcd_barrier(const XcdBarrier& b) {
;     ...
;             __builtin_amdgcn_fence(__ATOMIC_ACQUIRE, "agent");
;             xb_add(&bar[XB_XGEN(b.x)], 1u);
;             asm volatile("s_waitcnt vmcnt(0)" ::: "memory");
.LBB0_1108:
	s_or_b64 exec, exec, s[6:7]
	s_mov_b64 s[6:7], exec
	v_mbcnt_lo_u32_b32 v0, s6, 0
	v_mbcnt_hi_u32_b32 v0, s7, v0
	v_cmp_eq_u32_e32 vcc, 0, v0
	s_waitcnt vmcnt(0)
	buffer_inv sc1
	s_and_saveexec_b64 s[8:9], vcc
	s_cbranch_execz .LBB0_1110
	s_bcnt1_i32_b64 s6, s[6:7]
	v_mov_b32_e32 v0, 0x2000
	v_mov_b32_e32 v1, s6
.LBB0_1110:
	s_or_b64 exec, exec, s[8:9]
	s_waitcnt vmcnt(0)

; __device__ __forceinline__ unsigned xb_add(unsigned* p, unsigned v) { return __hip_atomic_fetch_add(p, v, __ATOMIC_RELAXED, __HIP_MEMORY_SCOPE_AGENT); }
; __device__ __forceinline__ void xcd_barrier(const XcdBarrier& b) {
;     ...
;             __builtin_amdgcn_fence(__ATOMIC_ACQUIRE, "agent");
;             xb_add(&bar[XB_XGEN(b.x)], 1u);
;             asm volatile("s_waitcnt vmcnt(0)" ::: "memory");
.LBB0_1204:
	s_or_b64 exec, exec, s[6:7]
	s_mov_b64 s[6:7], exec
	v_mbcnt_lo_u32_b32 v0, s6, 0
	v_mbcnt_hi_u32_b32 v0, s7, v0
	v_cmp_eq_u32_e32 vcc, 0, v0
	s_waitcnt vmcnt(0)
	buffer_inv sc1
	s_and_saveexec_b64 s[8:9], vcc
	s_cbranch_execz .LBB0_1206
	s_bcnt1_i32_b64 s6, s[6:7]
	v_mov_b32_e32 v0, 0x2000
	v_mov_b32_e32 v1, s6
.LBB0_1206:
	s_or_b64 exec, exec, s[8:9]
	s_waitcnt vmcnt(0)
